# P5 spatial-gating loop: static s_setprio 1 for waves 4-7 (plus the prompt-loop static priority)
# baseline (speedup 1.0000x reference)
; __device__ __forceinline__ bf16x8 tobf8(f32x8 x) { u32x4 w = {cvtpk(x[0], x[1]), cvtpk(x[2], x[3]), cvtpk(x[4], x[5]), cvtpk(x[6], x[7])}; return *reinterpret_cast<bf16x8*>(&w); }
; __device__ __forceinline__ void spatial_phase(const Params& p, char* lds) {
;     ...
;     for (; u < 1536; u += gridDim.x) {
;         SP_DECODE(u, samp, g, cidx, rbase, nrows)
;         const bool act = samp ? (tb == 0) : true; const int nit = samp ? 4 : 8;
;         if (g != g_loaded) { g_loaded = g;
; #pragma unroll
;             for (int st_ = 0; st_ < 2; ++st_)
; #pragma unroll
;                 for (int ks = 0; ks < 4; ++ks) { const int s0 = 64 * st_ + 16 * ks + 8 * hi; const float* wp = p.w_sp + ((size_t)g * CCH + t) * CCH + s0;
;                     const f32x4 a = *(const f32x4*)wp, c = *(const f32x4*)(wp + 4); f32x8 y;
; #pragma unroll
;                     for (int i = 0; i < 4; ++i) { y[i] = (s0 + i <= t) ? a[i] : 0.f; y[4 + i] = (s0 + 4 + i <= t) ? c[i] : 0.f; }
;                     pa[st_][ks] = tobf8(y); }
.LBB0_1199:
	s_andn2_b64 vcc, exec, s[72:73]
	s_barrier
	s_cbranch_vccz .LBB0_1268
.LBB0_1200:
	v_readfirstlane_b32 s98, v183
	s_cmpk_lt_u32 s98, 0x100
	s_cbranch_scc1 .Lsp_10
	s_setprio 1
.Lsp_10:
	s_and_b32 s42, s79, 15
	s_cmp_eq_u32 s42, s33
	s_cbranch_scc1 .LBB0_1202
	v_lshl_or_b32 v0, s42, 16, v209
	v_mov_b32_e32 v1, v96
	v_lshl_add_u64 v[0:1], v[224:225], 0, v[0:1]
	global_load_dwordx4 v[24:27], v[0:1], off
	global_load_dwordx4 v[28:31], v[0:1], off offset:16
	global_load_dwordx4 v[32:35], v[0:1], off offset:64
	global_load_dwordx4 v[36:39], v[0:1], off offset:80
	global_load_dwordx4 v[40:43], v[0:1], off offset:128
	global_load_dwordx4 v[44:47], v[0:1], off offset:144
	global_load_dwordx4 v[48:51], v[0:1], off offset:192
	global_load_dwordx4 v[52:55], v[0:1], off offset:208
	global_load_dwordx4 v[56:59], v[0:1], off offset:256
	global_load_dwordx4 v[60:63], v[0:1], off offset:272
	global_load_dwordx4 v[100:103], v[0:1], off offset:320
	global_load_dwordx4 v[104:107], v[0:1], off offset:336
	global_load_dwordx4 v[108:111], v[0:1], off offset:384
	global_load_dwordx4 v[112:115], v[0:1], off offset:400
	global_load_dwordx4 v[116:119], v[0:1], off offset:448
	global_load_dwordx4 v[120:123], v[0:1], off offset:464
	s_waitcnt vmcnt(0)
	v_readlane_b32 s38, v253, 16
	v_readlane_b32 s39, v253, 17
	v_readlane_b32 s52, v253, 0
	v_readlane_b32 s53, v253, 1
	s_mov_b32 s33, s42
	v_readlane_b32 s54, v253, 2
	v_readlane_b32 s55, v253, 3
	v_readlane_b32 s56, v253, 4
	v_readlane_b32 s57, v253, 5
	v_readlane_b32 s58, v253, 6
	v_readlane_b32 s59, v253, 7
	v_mov_b32_e32 v2, v24
	v_mov_b32_e32 v3, v25
	v_mov_b32_e32 v4, v26
	v_mov_b32_e32 v5, v27
	v_cndmask_b32_e64 v2, v2, 0, s[38:39]
	v_readlane_b32 s38, v253, 53
	v_readlane_b32 s39, v253, 54
	v_mov_b32_e32 v6, v28
	v_mov_b32_e32 v7, v29
	v_mov_b32_e32 v8, v30
	v_mov_b32_e32 v9, v31
	s_nop 0
	v_cndmask_b32_e64 v6, v6, 0, s[38:39]
	v_readlane_b32 s38, v253, 57
	v_readlane_b32 s39, v253, 58
	s_nop 1
	v_cndmask_b32_e64 v3, 0, v3, s[38:39]
	v_readlane_b32 s38, v253, 59
	v_readlane_b32 s39, v253, 60
	v_cvt_pk_bf16_f32 v132, v2, v3
	s_nop 1
	v_cndmask_b32_e64 v7, v7, 0, s[38:39]
	v_readlane_b32 s38, v253, 61
	v_readlane_b32 s39, v253, 62
	s_nop 1
	v_cndmask_b32_e64 v4, v4, 0, s[38:39]
	v_readlane_b32 s38, v253, 63
	v_readlane_b32 s39, v254, 0
	s_nop 1
	v_cndmask_b32_e64 v8, v8, 0, s[38:39]
	v_readlane_b32 s38, v254, 1
	v_readlane_b32 s39, v254, 2
	s_nop 1
	v_cndmask_b32_e64 v5, v5, 0, s[38:39]
	v_readlane_b32 s38, v254, 3
	v_readlane_b32 s39, v254, 4
	v_cvt_pk_bf16_f32 v133, v4, v5
	v_cvt_pk_bf16_f32 v134, v6, v7
	s_nop 1
	v_cndmask_b32_e64 v9, v9, 0, s[38:39]
	v_cvt_pk_bf16_f32 v135, v8, v9
	v_readlane_b32 s38, v254, 5
	v_readlane_b32 s39, v254, 6
	v_mov_b32_e32 v2, v32
	v_mov_b32_e32 v3, v33
	v_mov_b32_e32 v4, v34
	v_mov_b32_e32 v5, v35
	s_nop 0
	v_cndmask_b32_e64 v2, v2, 0, s[38:39]
	v_readlane_b32 s38, v253, 55
	v_readlane_b32 s39, v253, 56
	v_mov_b32_e32 v6, v36
	v_mov_b32_e32 v7, v37
	v_mov_b32_e32 v8, v38
	v_mov_b32_e32 v9, v39
	s_nop 0
	v_cndmask_b32_e64 v6, v6, 0, s[38:39]
	v_readlane_b32 s38, v254, 7
	v_readlane_b32 s39, v254, 8
	s_nop 1
	v_cndmask_b32_e64 v3, v3, 0, s[38:39]
	v_readlane_b32 s38, v254, 9
	v_readlane_b32 s39, v254, 10
	v_cvt_pk_bf16_f32 v136, v2, v3
	s_nop 1
	v_cndmask_b32_e64 v7, v7, 0, s[38:39]
	v_readlane_b32 s38, v254, 11
	v_readlane_b32 s39, v254, 12
	s_nop 1
	v_cndmask_b32_e64 v4, v4, 0, s[38:39]
	v_readlane_b32 s38, v254, 13
	v_readlane_b32 s39, v254, 14
	s_nop 1
	v_cndmask_b32_e64 v8, v8, 0, s[38:39]
	v_readlane_b32 s38, v254, 15
	v_readlane_b32 s39, v254, 16
	s_nop 1
	v_cndmask_b32_e64 v5, v5, 0, s[38:39]
	v_readlane_b32 s38, v253, 49
	v_readlane_b32 s39, v253, 50
	v_cvt_pk_bf16_f32 v137, v4, v5
	v_cvt_pk_bf16_f32 v138, v6, v7
	s_nop 1
	v_cndmask_b32_e64 v9, v9, 0, s[38:39]
	v_cvt_pk_bf16_f32 v139, v8, v9
	v_readlane_b32 s38, v254, 17
	v_readlane_b32 s39, v254, 18
	v_mov_b32_e32 v2, v40
	v_mov_b32_e32 v3, v41
	v_mov_b32_e32 v4, v42
	v_mov_b32_e32 v5, v43
	s_nop 0
	v_cndmask_b32_e64 v2, v2, 0, s[38:39]
	v_readlane_b32 s38, v253, 51
	v_readlane_b32 s39, v253, 52
	v_mov_b32_e32 v6, v44
	v_mov_b32_e32 v7, v45
	v_mov_b32_e32 v8, v46
	v_mov_b32_e32 v9, v47
	s_nop 0
	v_cndmask_b32_e64 v6, v6, 0, s[38:39]
	v_readlane_b32 s38, v254, 19
	v_readlane_b32 s39, v254, 20
	s_nop 1
	v_cndmask_b32_e64 v3, v3, 0, s[38:39]
	v_readlane_b32 s38, v254, 21
	v_readlane_b32 s39, v254, 22
	v_cvt_pk_bf16_f32 v140, v2, v3
	s_nop 1
	v_cndmask_b32_e64 v7, v7, 0, s[38:39]
	v_readlane_b32 s38, v254, 23
	v_readlane_b32 s39, v254, 24
	s_nop 1
	v_cndmask_b32_e64 v4, v4, 0, s[38:39]
	v_readlane_b32 s38, v254, 25
	v_readlane_b32 s39, v254, 26
	s_nop 1
	v_cndmask_b32_e64 v8, v8, 0, s[38:39]
	v_readlane_b32 s38, v254, 27
	v_readlane_b32 s39, v254, 28
	s_nop 1
	v_cndmask_b32_e64 v5, v5, 0, s[38:39]
	v_readlane_b32 s38, v254, 29
; __device__ __forceinline__ int crow(int r, int hi) { return (r & 3) + 8 * (r >> 2) + 4 * hi; }
; __device__ __forceinline__ bf16x8 tobf8(f32x8 x) { u32x4 w = {cvtpk(x[0], x[1]), cvtpk(x[2], x[3]), cvtpk(x[4], x[5]), cvtpk(x[6], x[7])}; return *reinterpret_cast<bf16x8*>(&w); }
; __device__ __forceinline__ void spatial_phase(const Params& p, char* lds) {
;     ...
;                 for (int ks = 0; ks < 4; ++ks) { const int s0 = 64 * st_ + 16 * ks + 8 * hi; const float* wp = p.w_sp + ((size_t)g * CCH + t) * CCH + s0;
;                     const f32x4 a = *(const f32x4*)wp, c = *(const f32x4*)(wp + 4); f32x8 y;
; #pragma unroll
;                     for (int i = 0; i < 4; ++i) { y[i] = (s0 + i <= t) ? a[i] : 0.f; y[4 + i] = (s0 + 4 + i <= t) ? c[i] : 0.f; }
;                     pa[st_][ks] = tobf8(y); }
; #pragma unroll
;             for (int r = 0; r < 16; ++r) bsp_[r] = p.b_sp[g * CCH + 32 * tb + crow(r, hi)]; }
	v_readlane_b32 s39, v254, 30
	v_cvt_pk_bf16_f32 v141, v4, v5
	v_cvt_pk_bf16_f32 v142, v6, v7
	s_nop 1
	v_cndmask_b32_e64 v9, v9, 0, s[38:39]
	v_cvt_pk_bf16_f32 v143, v8, v9
	v_readlane_b32 s38, v254, 31
	v_readlane_b32 s39, v254, 32
	v_mov_b32_e32 v2, v48
	v_mov_b32_e32 v3, v49
	v_mov_b32_e32 v4, v50
	v_mov_b32_e32 v5, v51
	s_nop 0
	v_cndmask_b32_e64 v2, v2, 0, s[38:39]
	v_readlane_b32 s38, v254, 33
	v_readlane_b32 s39, v254, 34
	v_mov_b32_e32 v6, v52
	v_mov_b32_e32 v7, v53
	v_mov_b32_e32 v8, v54
	v_mov_b32_e32 v9, v55
	s_nop 0
	v_cndmask_b32_e64 v6, v6, 0, s[38:39]
	v_readlane_b32 s38, v254, 35
	v_readlane_b32 s39, v254, 36
	s_nop 1
	v_cndmask_b32_e64 v3, v3, 0, s[38:39]
	v_readlane_b32 s38, v254, 37
	v_readlane_b32 s39, v254, 38
	v_cvt_pk_bf16_f32 v144, v2, v3
	s_nop 1
	v_cndmask_b32_e64 v7, v7, 0, s[38:39]
	v_readlane_b32 s38, v254, 39
	v_readlane_b32 s39, v254, 40
	s_nop 1
	v_cndmask_b32_e64 v4, v4, 0, s[38:39]
	v_readlane_b32 s38, v254, 41
	v_readlane_b32 s39, v254, 42
	s_nop 1
	v_cndmask_b32_e64 v8, v8, 0, s[38:39]
	v_readlane_b32 s38, v254, 43
	v_readlane_b32 s39, v254, 44
	s_nop 1
	v_cndmask_b32_e64 v5, v5, 0, s[38:39]
	v_readlane_b32 s38, v254, 45
	v_readlane_b32 s39, v254, 46
	v_cvt_pk_bf16_f32 v145, v4, v5
	v_cvt_pk_bf16_f32 v146, v6, v7
	s_nop 1
	v_cndmask_b32_e64 v9, v9, 0, s[38:39]
	v_cvt_pk_bf16_f32 v147, v8, v9
	v_readlane_b32 s38, v254, 47
	v_readlane_b32 s39, v254, 48
	v_mov_b32_e32 v2, v56
	v_mov_b32_e32 v3, v57
	v_mov_b32_e32 v4, v58
	v_mov_b32_e32 v5, v59
	s_nop 0
	v_cndmask_b32_e64 v2, v2, 0, s[38:39]
	v_readlane_b32 s38, v254, 49
	v_readlane_b32 s39, v254, 50
	v_mov_b32_e32 v6, v60
	v_mov_b32_e32 v7, v61
	v_mov_b32_e32 v8, v62
	v_mov_b32_e32 v9, v63
	s_nop 0
	v_cndmask_b32_e64 v6, v6, 0, s[38:39]
	v_readlane_b32 s38, v254, 51
	v_readlane_b32 s39, v254, 52
	s_nop 1
	v_cndmask_b32_e64 v3, v3, 0, s[38:39]
	v_readlane_b32 s38, v254, 53
	v_readlane_b32 s39, v254, 54
	v_cvt_pk_bf16_f32 v148, v2, v3
	s_nop 1
	v_cndmask_b32_e64 v7, v7, 0, s[38:39]
	v_readlane_b32 s38, v254, 55
	v_readlane_b32 s39, v254, 56
	s_nop 1
	v_cndmask_b32_e64 v4, v4, 0, s[38:39]
	v_readlane_b32 s38, v254, 57
	v_readlane_b32 s39, v254, 58
	s_nop 1
	v_cndmask_b32_e64 v8, v8, 0, s[38:39]
	v_readlane_b32 s38, v254, 59
	v_readlane_b32 s39, v254, 60
	s_nop 1
	v_cndmask_b32_e64 v5, v5, 0, s[38:39]
	v_readlane_b32 s38, v254, 61
	v_readlane_b32 s39, v254, 62
	v_cvt_pk_bf16_f32 v149, v4, v5
	v_cvt_pk_bf16_f32 v150, v6, v7
	s_nop 1
	v_cndmask_b32_e64 v9, v9, 0, s[38:39]
	v_cvt_pk_bf16_f32 v151, v8, v9
	v_readlane_b32 s38, v254, 63
	v_readlane_b32 s39, v255, 0
	v_mov_b32_e32 v2, v100
	v_mov_b32_e32 v3, v101
	v_mov_b32_e32 v4, v102
	v_mov_b32_e32 v5, v103
	v_cndmask_b32_e64 v4, v4, 0, s[84:85]
	v_cndmask_b32_e64 v2, v2, 0, s[38:39]
	v_readlane_b32 s38, v255, 1
	v_readlane_b32 s39, v255, 2
	v_mov_b32_e32 v6, v104
	v_mov_b32_e32 v7, v105
	v_mov_b32_e32 v8, v106
	v_mov_b32_e32 v9, v107
	v_cndmask_b32_e64 v7, v7, 0, s[50:51]
	v_cndmask_b32_e64 v8, v8, 0, s[88:89]
	v_cndmask_b32_e64 v6, v6, 0, s[38:39]
	v_readlane_b32 s38, v255, 3
	v_readlane_b32 s39, v255, 4
	v_cndmask_b32_e64 v5, v5, 0, s[96:97]
	v_cndmask_b32_e64 v9, v9, 0, s[0:1]
	v_cndmask_b32_e64 v3, v3, 0, s[38:39]
	v_cvt_pk_bf16_f32 v152, v2, v3
	v_cvt_pk_bf16_f32 v153, v4, v5
	v_cvt_pk_bf16_f32 v154, v6, v7
	v_cvt_pk_bf16_f32 v155, v8, v9
	v_mov_b32_e32 v2, v108
	v_mov_b32_e32 v3, v109
	v_mov_b32_e32 v4, v110
	v_mov_b32_e32 v5, v111
	v_cndmask_b32_e64 v2, v2, 0, s[2:3]
	v_mov_b32_e32 v6, v112
	v_mov_b32_e32 v7, v113
	v_mov_b32_e32 v8, v114
	v_mov_b32_e32 v9, v115
	v_cndmask_b32_e64 v6, v6, 0, s[4:5]
	v_cndmask_b32_e64 v3, v3, 0, s[6:7]
	v_cndmask_b32_e64 v7, v7, 0, s[8:9]
	v_cndmask_b32_e64 v4, v4, 0, s[10:11]
	v_cndmask_b32_e64 v8, v8, 0, s[12:13]
	v_cndmask_b32_e64 v5, v5, 0, s[14:15]
	v_cndmask_b32_e64 v9, v9, 0, s[16:17]
	v_cvt_pk_bf16_f32 v156, v2, v3
	v_cvt_pk_bf16_f32 v157, v4, v5
	v_cvt_pk_bf16_f32 v158, v6, v7
	v_cvt_pk_bf16_f32 v159, v8, v9
	v_lshl_or_b32 v0, s42, 9, v211
	v_mov_b32_e32 v2, v116
	v_mov_b32_e32 v3, v117
	v_mov_b32_e32 v4, v118
	v_mov_b32_e32 v5, v119
	v_cndmask_b32_e64 v1, v2, 0, s[18:19]
	v_mov_b32_e32 v6, v120
	v_mov_b32_e32 v7, v121
	v_mov_b32_e32 v8, v122
	v_mov_b32_e32 v9, v123
	v_cndmask_b32_e64 v2, v6, 0, s[20:21]
	v_cndmask_b32_e64 v3, v3, 0, s[22:23]
	v_cndmask_b32_e64 v6, v7, 0, s[24:25]
	v_cndmask_b32_e64 v4, v4, 0, s[26:27]
	v_cndmask_b32_e64 v7, v8, 0, s[28:29]
	v_cndmask_b32_e64 v5, v5, 0, s[30:31]
	v_cndmask_b32_e64 v8, v9, 0, s[34:35]
	v_cvt_pk_bf16_f32 v160, v1, v3
	v_cvt_pk_bf16_f32 v161, v4, v5
	v_cvt_pk_bf16_f32 v162, v2, v6
	v_cvt_pk_bf16_f32 v163, v7, v8
	global_load_dwordx4 v[164:167], v0, s[52:53]
	global_load_dwordx4 v[168:171], v0, s[52:53] offset:32
	global_load_dwordx4 v[172:175], v0, s[52:53] offset:64
	global_load_dwordx4 v[176:179], v0, s[52:53] offset:96

; __device__ __forceinline__ void spatial_phase(const Params& p, char* lds) {
;     ...
;         }
;         __syncthreads();
;     }
;     ...
; }
.LBB0_1268:
	s_setprio 0
	v_readlane_b32 s96, v253, 48
